# attention: V staging lane map changed so each 16-lane group writes 256 contiguous LDS bytes (bank-conflict-free ds_write_b128), V load pointer per-lane delta
# baseline (speedup 1.0000x reference)
; __device__ __forceinline__ int v_st(int k, int c) { const int kk = (k & ~0xC) | ((k & 4) << 1) | ((k & 8) >> 1); return ((kk >> 3) * 4 + (c >> 5)) * 512 + ((kk & 7) * 32 + (c & 31)) * 2; }
; __device__ __forceinline__ int v_rd_base(int lane) { return ((lane & 3) << 3) | (((lane >> 2) & 3) << 6) | (((lane >> 4) & 1) << 5) | (((lane >> 5) & 1) << 8); }
; #define SLOAD(i, k0) do { sr_[i].vs0 = LD8(&Vh[(long)((k0) + sr) * LDK + sc]); sr_[i].vs1 = LD8(&Vh[(long)((k0) + 32 + sr) * LDK + sc]); \
;     sr_[i].ks0 = LD8(&Kh[(long)((k0) + sr) * LDK + sc]); sr_[i].ks1 = LD8(&Kh[(long)((k0) + 32 + sr) * LDK + sc]); } while (0)
; #define SWRITE(b, i) do { *(bf16x8*)((char*)V_lds + (b) * SHM_V + vst0) = sr_[i].vs0;          \
;     *(bf16x8*)((char*)V_lds + (b) * SHM_V + vst1) = sr_[i].vs1; int kc = sc * 2;               \
;     *(bf16x8*)((char*)K_lds + (b) * SHM_K + KSWZ(sr, kc)) = sr_[i].ks0;                       \
;     *(bf16x8*)((char*)K_lds + (b) * SHM_K + KSWZ(32 + sr, kc)) = sr_[i].ks1; } while (0)
; #define SWAIT() asm volatile("s_waitcnt vmcnt(4)" ::: "memory")
; __device__ __forceinline__ void attn_body(const bf16_t* __restrict__ Qb, const bf16_t* __restrict__ Kh, const bf16_t* __restrict__ Vh, const bf16_t* __restrict__ Zb, ...
;     ...
;     float l_reg = 0; f32x16 o[4] = {}; bf16x8 qr[8];
;     const bf16_t* Qw = Qb + (long)(wid * QBLK + r32) * LDQ + hi * 8;
; #pragma unroll
;     for (int d0 = 0; d0 < 8; ++d0) qr[d0] = *reinterpret_cast<const bf16x8*>(Qw + d0 * 16);
;     const int sr = tid >> 4, sc = (tid & 15) * 8, vst0 = v_st(sr, sc), vst1 = v_st(32 + sr, sc);
;     const int vb0 = (int)(uintptr_t)V_lds + v_rd_base(lane);
;     struct { bf16x8 vs0, vs1, ks0, ks1; } sr_[2];
;     ...
;     SLOAD(0, 0); SLOAD(1, KVBLK);
;     ...
;     f32x16 pA0, pA1, pB0, pB1; bf16x8 pa0, pa1, pa2, pa3; const int NT = seq / KVBLK;
;     constexpr int SE = 0, SO = 1;
;     asm volatile("s_waitcnt vmcnt(0)" ::: "memory"); SWRITE(0, SE); __syncthreads();
;     qkt(pA0, pA1, K_lds, qr, r32, hi); partialSM(pA0, pA1, negBC);
;     SLOAD(SE, 2 * KVBLK);
;     SWAIT(); SWRITE(1, SO); __syncthreads();
;     if (__builtin_amdgcn_readfirstlane(tid) >= 256) __builtin_amdgcn_s_setprio(1);
;     for (int j = 1; j + 1 < NT; j += 2) {
.LBB0_489:
	v_and_b32_e32 v203, 63, v200
	v_exp_f32_e32 v235, v1
	v_lshlrev_b32_e32 v1, 4, v203
	v_exp_f32_e32 v233, v0
	v_exp_f32_e32 v231, v2
	v_lshlrev_b32_e32 v0, 3, v203
	v_and_b32_e32 v1, 0xc0, v1
	v_lshlrev_b32_e32 v2, 1, v203
	v_and_or_b32 v1, v0, 24, v1
	v_and_b32_e32 v2, 32, v2
	v_and_b32_e32 v0, 0x100, v0
	s_cmp_lg_u32 0, -1
	v_or3_b32 v0, v1, v2, v0
	s_cselect_b32 s42, 0, 0
	s_mov_b32 s23, s9
	v_add_u32_e32 v206, s42, v0
	s_addk_i32 s42, 0x4000
	v_add_u32_e32 v205, s42, v0
	v_lshl_add_u64 v[0:1], v[186:187], 0, s[22:23]
	v_exp_f32_e32 v234, v3
	v_exp_f32_e32 v230, v4
	v_exp_f32_e32 v232, v5
	v_exp_f32_e32 v228, v6
	v_exp_f32_e32 v229, v7
	v_exp_f32_e32 v225, v8
	v_exp_f32_e32 v227, v9
	v_exp_f32_e32 v224, v10
	v_exp_f32_e32 v226, v11
	v_exp_f32_e32 v221, v12
	v_exp_f32_e32 v223, v13
	v_exp_f32_e32 v181, v14
	v_exp_f32_e32 v222, v15
	v_mad_u64_u32 v[2:3], s[22:23], v0, s30, 0
	v_and_b32_e32 v0, 15, v200
	v_lshlrev_b32_e32 v0, 4, v0
	v_mad_i32_i24 v1, v1, s30, v3
	v_or3_b32 v0, v2, s41, v0
	v_mov_b32_e32 v204, 0
	s_mov_b32 s39, 4
	s_add_i32 s40, s33, -1
	v_lshl_add_u64 v[190:191], s[12:13], 0, v[0:1]
	v_mov_b32_e32 v0, 0
	v_mov_b32_e32 v1, v204
	v_mov_b32_e32 v2, v204
	v_mov_b32_e32 v3, v204
	v_mov_b32_e32 v4, v204
	v_mov_b32_e32 v5, v204
	v_mov_b32_e32 v6, v204
	v_mov_b32_e32 v7, v204
	v_mov_b32_e32 v8, v204
	v_mov_b32_e32 v9, v204
	v_mov_b32_e32 v10, v204
	v_mov_b32_e32 v11, v204
	v_mov_b32_e32 v12, v204
	v_mov_b32_e32 v13, v204
	v_mov_b32_e32 v14, v204
	v_mov_b32_e32 v15, v204
	v_mov_b32_e32 v16, 0
	v_mov_b32_e32 v17, v204
	v_mov_b32_e32 v18, v204
	v_mov_b32_e32 v19, v204
	v_mov_b32_e32 v20, v204
	v_mov_b32_e32 v21, v204
	v_mov_b32_e32 v22, v204
	v_mov_b32_e32 v23, v204
	v_mov_b32_e32 v24, v204
	v_mov_b32_e32 v25, v204
	v_mov_b32_e32 v26, v204
	v_mov_b32_e32 v27, v204
	v_mov_b32_e32 v28, v204
	v_mov_b32_e32 v29, v204
	v_mov_b32_e32 v30, v204
	v_mov_b32_e32 v31, v204
	v_mov_b32_e32 v32, 0
	v_mov_b32_e32 v33, v204
	v_mov_b32_e32 v34, v204
	v_mov_b32_e32 v35, v204
	v_mov_b32_e32 v36, v204
	v_mov_b32_e32 v37, v204
	v_mov_b32_e32 v38, v204
	v_mov_b32_e32 v39, v204
	v_mov_b32_e32 v40, v204
	v_mov_b32_e32 v41, v204
	v_mov_b32_e32 v42, v204
	v_mov_b32_e32 v43, v204
	v_mov_b32_e32 v44, v204
	v_mov_b32_e32 v45, v204
	v_mov_b32_e32 v46, v204
	v_mov_b32_e32 v47, v204
	v_mov_b32_e32 v48, 0
	v_mov_b32_e32 v49, v204
	v_mov_b32_e32 v50, v204
	v_mov_b32_e32 v51, v204
	v_mov_b32_e32 v52, v204
	v_mov_b32_e32 v53, v204
	v_mov_b32_e32 v54, v204
	v_mov_b32_e32 v55, v204
	v_mov_b32_e32 v56, v204
	v_mov_b32_e32 v57, v204
	v_mov_b32_e32 v58, v204
	v_mov_b32_e32 v59, v204
	v_mov_b32_e32 v60, v204
	v_mov_b32_e32 v61, v204
	v_mov_b32_e32 v62, v204
	v_mov_b32_e32 v63, v204
	v_exp_f32_e32 v64, v64
	v_exp_f32_e32 v65, v65
	v_exp_f32_e32 v66, v66
	v_exp_f32_e32 v67, v67
	v_exp_f32_e32 v68, v68
	v_exp_f32_e32 v69, v69
	v_exp_f32_e32 v70, v70
	v_exp_f32_e32 v71, v71
	v_exp_f32_e32 v72, v72
	v_exp_f32_e32 v73, v73
	v_exp_f32_e32 v74, v74
	v_exp_f32_e32 v75, v75
	v_exp_f32_e32 v76, v76
	v_exp_f32_e32 v77, v77
	v_exp_f32_e32 v78, v78
	v_exp_f32_e32 v79, v79
	s_mov_b32 s100, 0xfffa0000
	s_mov_b32 s101, -1
	s_mov_b32 s98, 0xfffd0000
	s_mov_b32 s99, -1
	v_bfe_u32 v219, v200, 2, 2
	v_bfe_u32 v220, v200, 7, 1
	v_lshl_or_b32 v219, v220, 2, v219
	v_bfe_u32 v220, v200, 6, 1
	v_lshl_or_b32 v219, v220, 3, v219
	v_bfe_u32 v220, v200, 8, 1
	v_lshl_or_b32 v219, v220, 4, v219
	v_lshrrev_b32_e32 v220, 4, v200
	v_sub_u32_e32 v219, v219, v220
	v_mul_i32_i24_e32 v219, 0x1800, v219
	v_bfe_u32 v220, v200, 4, 2
	v_lshl_add_u32 v219, v220, 6, v219
	v_and_b32_e32 v220, 3, v200
	v_lshl_add_u32 v219, v220, 4, v219
	v_and_b32_e32 v220, 15, v200
	v_lshlrev_b32_e32 v220, 4, v220
	v_sub_u32_e32 v252, v219, v220
	v_ashrrev_i32_e32 v253, 31, v252
	v_lshrrev_b32_e32 v219, 7, v200
	v_lshlrev_b32_e32 v207, 11, v219
	v_bfe_u32 v219, v200, 4, 2
	v_lshl_or_b32 v207, v219, 9, v207
	v_bfe_u32 v219, v200, 6, 1
	v_lshl_or_b32 v207, v219, 8, v207
	v_bfe_u32 v219, v200, 2, 2
	v_lshl_or_b32 v207, v219, 6, v207
	v_and_b32_e32 v219, 3, v200
	v_lshl_or_b32 v207, v219, 4, v207
	v_add_u32_e32 v208, 0x10000, v207
	v_lshl_add_u64 v[190:191], v[190:191], 0, s[100:101]
	s_mov_b32 s100, 0x60000
	s_mov_b32 s101, 0

; #define SBAR() __builtin_amdgcn_sched_barrier(0)
; #define SLOAD(i, k0) do { sr_[i].vs0 = LD8(&Vh[(long)((k0) + sr) * LDK + sc]); sr_[i].vs1 = LD8(&Vh[(long)((k0) + 32 + sr) * LDK + sc]); \
;     sr_[i].ks0 = LD8(&Kh[(long)((k0) + sr) * LDK + sc]); sr_[i].ks1 = LD8(&Kh[(long)((k0) + 32 + sr) * LDK + sc]); } while (0)
; #define SWAIT() asm volatile("s_waitcnt vmcnt(4)" ::: "memory")
; template <int OFF> __device__ __forceinline__ s16x4 tr_read(int vb) {
;     s16x4 r; asm volatile("ds_read_b64_tr_b16 %0, %1 offset:%2" : "=&v"(r) : "v"(vb), "i"(OFF) : "memory"); return r;
; }
; template <int D0> __device__ __forceinline__ void pv_one(f32x16& od, int vb, bf16x8 pa0, bf16x8 pa1, bf16x8 pa2, bf16x8 pa3) {
;     const s16x4 l0 = tr_read<v_rd_off(D0, 0, 0)>(vb), h0 = tr_read<v_rd_off(D0, 0, 1)>(vb), l1 = tr_read<v_rd_off(D0, 1, 0)>(vb), h1 = tr_read<v_rd_off(D0, 1, 1)>(vb);
;     const s16x4 l2 = tr_read<v_rd_off(D0, 2, 0)>(vb), h2 = tr_read<v_rd_off(D0, 2, 1)>(vb), l3 = tr_read<v_rd_off(D0, 3, 0)>(vb), h3 = tr_read<v_rd_off(D0, 3, 1)>(vb);
;     asm volatile("s_waitcnt lgkmcnt(0)" ::: "memory"); SBAR();
;     ...
;     od = __builtin_amdgcn_mfma_f32_32x32x16_bf16(pa0, PK(l0, h0), od, 0, 0, 0);
;     od = __builtin_amdgcn_mfma_f32_32x32x16_bf16(pa1, PK(l1, h1), od, 0, 0, 0);
;     od = __builtin_amdgcn_mfma_f32_32x32x16_bf16(pa2, PK(l2, h2), od, 0, 0, 0);
;     od = __builtin_amdgcn_mfma_f32_32x32x16_bf16(pa3, PK(l3, h3), od, 0, 0, 0);
;     ...
; }
; __device__ __forceinline__ void attn_body(const bf16_t* __restrict__ Qb, const bf16_t* __restrict__ Kh, const bf16_t* __restrict__ Vh, const bf16_t* __restrict__ Zb, ...
;     ...
;     for (int j = 1; j + 1 < NT; j += 2) {
;         SBAR(); qkt(pB0, pB1, (bf16_t*)((char*)K_lds + SHM_K), qr, r32, hi);
;         finishSM(pA0, pA1, 1.f, l_reg, pa0, pa1, pa2, pa3); SBAR();
;         SLOAD(SO, (j + 2) * KVBLK); SBAR();
;         pv_d0(o, vb0, pa0, pa1, pa2, pa3); partialSM(pB0, pB1, negBC);
;         __syncthreads(); SWAIT(); SWRITE(0, SE);
;         __syncthreads();
;         SBAR(); qkt(pA0, pA1, K_lds, qr, r32, hi);
;         finishSM(pB0, pB1, 1.f, l_reg, pa0, pa1, pa2, pa3); SBAR();
;         SLOAD(SE, ((j + 3 < NT) ? (j + 3) : (NT - 1)) * KVBLK); SBAR();
;         pv_d0(o, vb0 + (int)SHM_V, pa0, pa1, pa2, pa3); partialSM(pA0, pA1, negBC);
;         __syncthreads(); SWAIT(); SWRITE(1, SO);
.Lat2_noshift_A:
	s_waitcnt lgkmcnt(6)
	v_mfma_f32_32x32x16_bf16 v[0:15], v[160:163], v[236:239], v[0:15]
	ds_read_b64_tr_b16 v[236:237], v206 offset:512
	ds_read_b64_tr_b16 v[238:239], v206 offset:2560
	s_waitcnt lgkmcnt(6)
	v_mfma_f32_32x32x16_bf16 v[0:15], v[164:167], v[240:243], v[0:15]
	ds_read_b64_tr_b16 v[240:241], v206 offset:4608
	ds_read_b64_tr_b16 v[242:243], v206 offset:6656
	s_waitcnt vmcnt(0)
	ds_write_b128 v209, v[148:151] offset:32768
	v_exp_f32_e32 v181, v96
	v_exp_f32_e32 v221, v97
	s_waitcnt lgkmcnt(7)
	v_mfma_f32_32x32x16_bf16 v[0:15], v[168:171], v[244:247], v[0:15]
	ds_read_b64_tr_b16 v[244:245], v206 offset:8704
	ds_read_b64_tr_b16 v[246:247], v206 offset:10752
	ds_write_b128 v210, v[152:155] offset:32768
	v_exp_f32_e32 v222, v98
	v_exp_f32_e32 v223, v99
	s_waitcnt lgkmcnt(8)
	v_mfma_f32_32x32x16_bf16 v[0:15], v[172:175], v[248:251], v[0:15]
	ds_read_b64_tr_b16 v[248:249], v206 offset:12800
	ds_read_b64_tr_b16 v[250:251], v206 offset:14848
	ds_write_b128 v208, v[144:147] offset:16384
	v_exp_f32_e32 v224, v100
	v_exp_f32_e32 v225, v101
	s_waitcnt lgkmcnt(9)
	v_mfma_f32_32x32x16_bf16 v[16:31], v[160:163], v[236:239], v[16:31]
	ds_read_b64_tr_b16 v[236:237], v206 offset:1024
	ds_read_b64_tr_b16 v[238:239], v206 offset:3072
	ds_write_b128 v208, v[156:159] offset:24576
	v_exp_f32_e32 v226, v102
	v_exp_f32_e32 v227, v103
	s_waitcnt lgkmcnt(10)
	v_mfma_f32_32x32x16_bf16 v[16:31], v[164:167], v[240:243], v[16:31]
	ds_read_b64_tr_b16 v[240:241], v206 offset:5120
	ds_read_b64_tr_b16 v[242:243], v206 offset:7168
	v_exp_f32_e32 v228, v104
	v_exp_f32_e32 v229, v105
	s_waitcnt lgkmcnt(9)
	v_mfma_f32_32x32x16_bf16 v[16:31], v[168:171], v[244:247], v[16:31]
	ds_read_b64_tr_b16 v[244:245], v206 offset:9216
	ds_read_b64_tr_b16 v[246:247], v206 offset:11264
	v_lshl_add_u64 v[156:157], v[190:191], 0, v[252:253]
	v_lshl_add_u64 v[144:145], v[156:157], 0, s[98:99]
	global_load_dwordx4 v[156:159], v[156:157], off
	global_load_dwordx4 v[144:147], v[144:145], off
	v_exp_f32_e32 v230, v106
	v_exp_f32_e32 v231, v107
	s_waitcnt lgkmcnt(8)
	v_mfma_f32_32x32x16_bf16 v[16:31], v[172:175], v[248:251], v[16:31]
	ds_read_b64_tr_b16 v[248:249], v206 offset:13312
	ds_read_b64_tr_b16 v[250:251], v206 offset:15360
	v_exp_f32_e32 v232, v108
	v_exp_f32_e32 v233, v109
	s_waitcnt lgkmcnt(7)
	v_mfma_f32_32x32x16_bf16 v[32:47], v[160:163], v[236:239], v[32:47]
	ds_read_b64_tr_b16 v[236:237], v206 offset:1536
	ds_read_b64_tr_b16 v[238:239], v206 offset:3584
	v_lshl_add_u64 v[190:191], v[190:191], 0, s[100:101]
	v_lshl_add_u64 v[148:149], v[190:191], 0, s[98:99]
	global_load_dwordx4 v[152:155], v[190:191], off offset:-512
	global_load_dwordx4 v[148:151], v[148:149], off offset:-512
	v_exp_f32_e32 v234, v110
	v_exp_f32_e32 v235, v111
	s_waitcnt lgkmcnt(6)
	v_mfma_f32_32x32x16_bf16 v[32:47], v[164:167], v[240:243], v[32:47]
	ds_read_b64_tr_b16 v[240:241], v206 offset:5632
	ds_read_b64_tr_b16 v[242:243], v206 offset:7680
	v_exp_f32_e32 v80, v80
	v_exp_f32_e32 v81, v81
	s_waitcnt lgkmcnt(6)
	v_mfma_f32_32x32x16_bf16 v[32:47], v[168:171], v[244:247], v[32:47]
	ds_read_b64_tr_b16 v[244:245], v206 offset:9728
	ds_read_b64_tr_b16 v[246:247], v206 offset:11776
	v_exp_f32_e32 v82, v82
	v_exp_f32_e32 v83, v83
	s_waitcnt lgkmcnt(6)
	v_mfma_f32_32x32x16_bf16 v[32:47], v[172:175], v[248:251], v[32:47]
	ds_read_b64_tr_b16 v[248:249], v206 offset:13824
	ds_read_b64_tr_b16 v[250:251], v206 offset:15872
	v_exp_f32_e32 v84, v84
	v_exp_f32_e32 v85, v85
	s_waitcnt lgkmcnt(6)
	v_mfma_f32_32x32x16_bf16 v[48:63], v[160:163], v[236:239], v[48:63]
	v_exp_f32_e32 v86, v86
	v_exp_f32_e32 v87, v87
	s_waitcnt lgkmcnt(4)
	v_mfma_f32_32x32x16_bf16 v[48:63], v[164:167], v[240:243], v[48:63]
	v_exp_f32_e32 v88, v88
	v_exp_f32_e32 v89, v89
	v_exp_f32_e32 v90, v90
	s_waitcnt lgkmcnt(2)
	v_mfma_f32_32x32x16_bf16 v[48:63], v[168:171], v[244:247], v[48:63]
	v_exp_f32_e32 v91, v91
	v_exp_f32_e32 v92, v92
	v_exp_f32_e32 v93, v93
	s_waitcnt lgkmcnt(0)
	v_mfma_f32_32x32x16_bf16 v[48:63], v[172:175], v[248:251], v[48:63]
	v_exp_f32_e32 v94, v94
	v_exp_f32_e32 v95, v95
	v_mov_b32_e32 v208, v207
	s_waitcnt lgkmcnt(0)
	s_barrier
	ds_read_b128 v[236:239], v211 offset:32768
	ds_read_b128 v[240:243], v211 offset:40960
	ds_read_b128 v[244:247], v212 offset:32768
	ds_read_b128 v[248:251], v212 offset:40960
	v_add_f32_e32 v219, v181, v221
	v_cvt_pk_bf16_f32 v160, v181, v221
	v_add_f32_e32 v219, v222, v219
	s_waitcnt lgkmcnt(3)
	v_mfma_f32_32x32x16_bf16 v[96:111], v[236:239], v[116:119], 0
	v_cvt_pk_bf16_f32 v161, v222, v223
	v_add_f32_e32 v219, v223, v219
	v_cvt_pk_bf16_f32 v162, v224, v225
	v_add_f32_e32 v219, v224, v219
	v_cvt_pk_bf16_f32 v163, v226, v227
	s_waitcnt lgkmcnt(2)
	v_mfma_f32_32x32x16_bf16 v[64:79], v[240:243], v[116:119], 0
	ds_read_b128 v[236:239], v213 offset:32768
	ds_read_b128 v[240:243], v213 offset:40960
	v_add_f32_e32 v219, v225, v219
	v_cvt_pk_bf16_f32 v164, v228, v229
	v_add_f32_e32 v219, v226, v219
	v_cvt_pk_bf16_f32 v165, v230, v231
	v_add_f32_e32 v219, v227, v219
	s_waitcnt lgkmcnt(3)
	v_mfma_f32_32x32x16_bf16 v[96:111], v[244:247], v[124:127], v[96:111]
	v_cvt_pk_bf16_f32 v166, v232, v233
	v_add_f32_e32 v219, v228, v219
	v_cvt_pk_bf16_f32 v167, v234, v235
	v_add_f32_e32 v219, v229, v219
	s_waitcnt lgkmcnt(2)
	v_mfma_f32_32x32x16_bf16 v[64:79], v[248:251], v[124:127], v[64:79]
	ds_read_b128 v[244:247], v214 offset:32768
	ds_read_b128 v[248:251], v214 offset:40960
	v_cvt_pk_bf16_f32 v168, v80, v81
	v_add_f32_e32 v219, v230, v219
	v_cvt_pk_bf16_f32 v169, v82, v83
	v_add_f32_e32 v219, v231, v219
	s_waitcnt lgkmcnt(3)
; __device__ __forceinline__ void partialSM(f32x16& p0, f32x16& p1, float shift) {
;     if (shift != 0.f) { for (int r = 0; r < 16; ++r) { p0[r] += shift; p1[r] += shift; } }
;     for (int r = 0; r < 16; ++r) p0[r] = __builtin_amdgcn_exp2f(p0[r]);
; }
; __device__ __forceinline__ void finishSM(f32x16& p0, f32x16& p1, float alpha, float& l_reg, bf16x8& pa0, bf16x8& pa1, bf16x8& pa2, bf16x8& pa3) {
;     for (int r = 0; r < 16; ++r) p1[r] = __builtin_amdgcn_exp2f(p1[r]);
;     float ps = 0; for (int r = 0; r < 16; ++r) ps += p0[r]; for (int r = 0; r < 16; ++r) ps += p1[r];
;     { auto rr = __builtin_amdgcn_permlane32_swap(__float_as_uint(ps), __float_as_uint(ps), false, false);
;       ps = __uint_as_float(rr[0]) + __uint_as_float(rr[1]); }
;     l_reg = l_reg * alpha + ps;
;     ...
;     PK4(p0, 0, pa0); PK4(p0, 8, pa1); PK4(p1, 0, pa2); PK4(p1, 8, pa3);
;     ...
; }
; __device__ __forceinline__ void qkt(f32x16& p0, f32x16& p1, const bf16_t* Ks, const bf16x8* qr, int r32, int hi) {
;     p0 = f32x16{}; p1 = f32x16{};
;     for (int d0 = 0; d0 < 8; ++d0) { int cb = (d0 * 16 + hi * 8) * 2;
;         bf16x8 b0 = *reinterpret_cast<const bf16x8*>((const char*)Ks + KSWZ(r32, cb));
;         bf16x8 b1 = *reinterpret_cast<const bf16x8*>((const char*)Ks + KSWZ(32 + r32, cb));
;         p0 = __builtin_amdgcn_mfma_f32_32x32x16_bf16(b0, qr[d0], p0, 0, 0, 0);
;         p1 = __builtin_amdgcn_mfma_f32_32x32x16_bf16(b1, qr[d0], p1, 0, 0, 0); }
; }
	v_mfma_f32_32x32x16_bf16 v[96:111], v[236:239], v[112:115], v[96:111]
	v_cvt_pk_bf16_f32 v170, v84, v85
	v_add_f32_e32 v219, v232, v219
	v_cvt_pk_bf16_f32 v171, v86, v87
	v_add_f32_e32 v219, v233, v219
	s_waitcnt lgkmcnt(2)
	v_mfma_f32_32x32x16_bf16 v[64:79], v[240:243], v[112:115], v[64:79]
	ds_read_b128 v[236:239], v215 offset:32768
	ds_read_b128 v[240:243], v215 offset:40960
	v_cvt_pk_bf16_f32 v172, v88, v89
	v_add_f32_e32 v219, v234, v219
	v_cvt_pk_bf16_f32 v173, v90, v91
	v_add_f32_e32 v219, v235, v219
	s_waitcnt lgkmcnt(3)
	v_mfma_f32_32x32x16_bf16 v[96:111], v[244:247], v[120:123], v[96:111]
	v_cvt_pk_bf16_f32 v174, v92, v93
	v_add_f32_e32 v219, v80, v219
	v_cvt_pk_bf16_f32 v175, v94, v95
	v_add_f32_e32 v219, v81, v219
	s_waitcnt lgkmcnt(2)
	v_mfma_f32_32x32x16_bf16 v[64:79], v[248:251], v[120:123], v[64:79]
	ds_read_b128 v[244:247], v216 offset:32768
	ds_read_b128 v[248:251], v216 offset:40960
	v_permlane32_swap_b32_e32 v160, v162
	v_add_f32_e32 v219, v82, v219
	s_waitcnt lgkmcnt(3)
	v_mfma_f32_32x32x16_bf16 v[96:111], v[236:239], v[132:135], v[96:111]
	v_permlane32_swap_b32_e32 v161, v163
	v_add_f32_e32 v219, v83, v219
	v_permlane32_swap_b32_e32 v164, v166
	s_waitcnt lgkmcnt(2)
	v_mfma_f32_32x32x16_bf16 v[64:79], v[240:243], v[132:135], v[64:79]
	ds_read_b128 v[236:239], v217 offset:32768
	ds_read_b128 v[240:243], v217 offset:40960
	v_add_f32_e32 v219, v84, v219
	v_permlane32_swap_b32_e32 v165, v167
	v_add_f32_e32 v219, v85, v219
	s_waitcnt lgkmcnt(3)
	v_mfma_f32_32x32x16_bf16 v[96:111], v[244:247], v[140:143], v[96:111]
	v_permlane32_swap_b32_e32 v168, v170
	v_add_f32_e32 v219, v86, v219
	s_waitcnt lgkmcnt(2)
	v_mfma_f32_32x32x16_bf16 v[64:79], v[248:251], v[140:143], v[64:79]
	ds_read_b128 v[244:247], v218 offset:32768
	ds_read_b128 v[248:251], v218 offset:40960
	v_permlane32_swap_b32_e32 v169, v171
	v_add_f32_e32 v219, v87, v219
	v_permlane32_swap_b32_e32 v172, v174
	s_waitcnt lgkmcnt(3)
	v_mfma_f32_32x32x16_bf16 v[96:111], v[236:239], v[128:131], v[96:111]
	v_add_f32_e32 v219, v88, v219
	v_permlane32_swap_b32_e32 v173, v175
	v_add_f32_e32 v219, v89, v219
	s_waitcnt lgkmcnt(2)
	v_mfma_f32_32x32x16_bf16 v[64:79], v[240:243], v[128:131], v[64:79]
	ds_read_b64_tr_b16 v[236:237], v205 offset:0
	ds_read_b64_tr_b16 v[238:239], v205 offset:2048
	ds_read_b64_tr_b16 v[240:241], v205 offset:4096
	ds_read_b64_tr_b16 v[242:243], v205 offset:6144
	v_add_f32_e32 v219, v90, v219
	v_add_f32_e32 v219, v91, v219
	v_add_f32_e32 v219, v92, v219
	v_add_f32_e32 v219, v93, v219
	s_waitcnt lgkmcnt(5)
	v_mfma_f32_32x32x16_bf16 v[96:111], v[244:247], v[136:139], v[96:111]
	v_add_f32_e32 v219, v94, v219
	v_add_f32_e32 v219, v95, v219
	v_mov_b32_e32 v220, v219
	s_nop 1
	s_waitcnt lgkmcnt(4)
	v_mfma_f32_32x32x16_bf16 v[64:79], v[248:251], v[136:139], v[64:79]
	v_permlane32_swap_b32_e32 v219, v220
	v_add_f32_e32 v219, v219, v220
	v_add_f32_e32 v204, v204, v219
	ds_read_b64_tr_b16 v[244:245], v205 offset:8192
	ds_read_b64_tr_b16 v[246:247], v205 offset:10240
	ds_read_b64_tr_b16 v[248:249], v205 offset:12288
	ds_read_b64_tr_b16 v[250:251], v205 offset:14336
	s_and_b64 vcc, exec, s[6:7]
	s_cbranch_vccnz .Lat2_noshift_B
	s_nop 15
	v_pk_add_f32 v[110:111], v[182:183], v[110:111]
	v_pk_add_f32 v[108:109], v[182:183], v[108:109]
	v_pk_add_f32 v[106:107], v[182:183], v[106:107]
	v_pk_add_f32 v[104:105], v[182:183], v[104:105]
	v_pk_add_f32 v[102:103], v[182:183], v[102:103]
	v_pk_add_f32 v[100:101], v[182:183], v[100:101]
	v_pk_add_f32 v[98:99], v[182:183], v[98:99]
	v_pk_add_f32 v[96:97], v[182:183], v[96:97]
	v_pk_add_f32 v[78:79], v[182:183], v[78:79]
	v_pk_add_f32 v[76:77], v[182:183], v[76:77]
	v_pk_add_f32 v[74:75], v[182:183], v[74:75]
	v_pk_add_f32 v[72:73], v[182:183], v[72:73]
	v_pk_add_f32 v[70:71], v[182:183], v[70:71]
	v_pk_add_f32 v[68:69], v[182:183], v[68:69]
	v_pk_add_f32 v[66:67], v[182:183], v[66:67]
	v_pk_add_f32 v[64:65], v[182:183], v[64:65]
; #define SBAR() __builtin_amdgcn_sched_barrier(0)
; #define SLOAD(i, k0) do { sr_[i].vs0 = LD8(&Vh[(long)((k0) + sr) * LDK + sc]); sr_[i].vs1 = LD8(&Vh[(long)((k0) + 32 + sr) * LDK + sc]); \
;     sr_[i].ks0 = LD8(&Kh[(long)((k0) + sr) * LDK + sc]); sr_[i].ks1 = LD8(&Kh[(long)((k0) + 32 + sr) * LDK + sc]); } while (0)
; #define SWRITE(b, i) do { *(bf16x8*)((char*)V_lds + (b) * SHM_V + vst0) = sr_[i].vs0;          \
;     *(bf16x8*)((char*)V_lds + (b) * SHM_V + vst1) = sr_[i].vs1; int kc = sc * 2;               \
;     *(bf16x8*)((char*)K_lds + (b) * SHM_K + KSWZ(sr, kc)) = sr_[i].ks0;                       \
;     *(bf16x8*)((char*)K_lds + (b) * SHM_K + KSWZ(32 + sr, kc)) = sr_[i].ks1; } while (0)
; #define SWAIT() asm volatile("s_waitcnt vmcnt(4)" ::: "memory")
; template <int OFF> __device__ __forceinline__ s16x4 tr_read(int vb) {
;     s16x4 r; asm volatile("ds_read_b64_tr_b16 %0, %1 offset:%2" : "=&v"(r) : "v"(vb), "i"(OFF) : "memory"); return r;
; }
; template <int D0> __device__ __forceinline__ void pv_one(f32x16& od, int vb, bf16x8 pa0, bf16x8 pa1, bf16x8 pa2, bf16x8 pa3) {
;     const s16x4 l0 = tr_read<v_rd_off(D0, 0, 0)>(vb), h0 = tr_read<v_rd_off(D0, 0, 1)>(vb), l1 = tr_read<v_rd_off(D0, 1, 0)>(vb), h1 = tr_read<v_rd_off(D0, 1, 1)>(vb);
;     const s16x4 l2 = tr_read<v_rd_off(D0, 2, 0)>(vb), h2 = tr_read<v_rd_off(D0, 2, 1)>(vb), l3 = tr_read<v_rd_off(D0, 3, 0)>(vb), h3 = tr_read<v_rd_off(D0, 3, 1)>(vb);
;     asm volatile("s_waitcnt lgkmcnt(0)" ::: "memory"); SBAR();
;     ...
;     od = __builtin_amdgcn_mfma_f32_32x32x16_bf16(pa0, PK(l0, h0), od, 0, 0, 0);
;     od = __builtin_amdgcn_mfma_f32_32x32x16_bf16(pa1, PK(l1, h1), od, 0, 0, 0);
;     od = __builtin_amdgcn_mfma_f32_32x32x16_bf16(pa2, PK(l2, h2), od, 0, 0, 0);
;     od = __builtin_amdgcn_mfma_f32_32x32x16_bf16(pa3, PK(l3, h3), od, 0, 0, 0);
;     ...
; }
; __device__ __forceinline__ void attn_body(const bf16_t* __restrict__ Qb, const bf16_t* __restrict__ Kh, const bf16_t* __restrict__ Vh, const bf16_t* __restrict__ Zb, ...
;     ...
;         SBAR(); qkt(pA0, pA1, K_lds, qr, r32, hi);
;         finishSM(pB0, pB1, 1.f, l_reg, pa0, pa1, pa2, pa3); SBAR();
;         SLOAD(SE, ((j + 3 < NT) ? (j + 3) : (NT - 1)) * KVBLK); SBAR();
;         pv_d0(o, vb0 + (int)SHM_V, pa0, pa1, pa2, pa3); partialSM(pA0, pA1, negBC);
;         __syncthreads(); SWAIT(); SWRITE(1, SO);
;         __syncthreads();
;     }
.Lat2_noshift_B:
	s_waitcnt lgkmcnt(6)
	v_mfma_f32_32x32x16_bf16 v[0:15], v[160:163], v[236:239], v[0:15]
	ds_read_b64_tr_b16 v[236:237], v205 offset:512
	ds_read_b64_tr_b16 v[238:239], v205 offset:2560
	s_waitcnt lgkmcnt(6)
	v_mfma_f32_32x32x16_bf16 v[0:15], v[164:167], v[240:243], v[0:15]
	ds_read_b64_tr_b16 v[240:241], v205 offset:4608
	ds_read_b64_tr_b16 v[242:243], v205 offset:6656
	s_waitcnt vmcnt(0)
	ds_write_b128 v209, v[148:151] offset:49152
	v_exp_f32_e32 v233, v96
	v_exp_f32_e32 v235, v97
	s_waitcnt lgkmcnt(7)
	v_mfma_f32_32x32x16_bf16 v[0:15], v[168:171], v[244:247], v[0:15]
	ds_read_b64_tr_b16 v[244:245], v205 offset:8704
	ds_read_b64_tr_b16 v[246:247], v205 offset:10752
	ds_write_b128 v210, v[152:155] offset:49152
	v_exp_f32_e32 v231, v98
	v_exp_f32_e32 v234, v99
	s_waitcnt lgkmcnt(8)
	v_mfma_f32_32x32x16_bf16 v[0:15], v[172:175], v[248:251], v[0:15]
	ds_read_b64_tr_b16 v[248:249], v205 offset:12800
	ds_read_b64_tr_b16 v[250:251], v205 offset:14848
	ds_write_b128 v207, v[144:147] offset:0
	v_exp_f32_e32 v230, v100
	v_exp_f32_e32 v232, v101
	s_waitcnt lgkmcnt(9)
	v_mfma_f32_32x32x16_bf16 v[16:31], v[160:163], v[236:239], v[16:31]
	ds_read_b64_tr_b16 v[236:237], v205 offset:1024
	ds_read_b64_tr_b16 v[238:239], v205 offset:3072
	ds_write_b128 v207, v[156:159] offset:8192
	v_exp_f32_e32 v228, v102
	v_exp_f32_e32 v229, v103
	s_waitcnt lgkmcnt(10)
	v_mfma_f32_32x32x16_bf16 v[16:31], v[164:167], v[240:243], v[16:31]
	ds_read_b64_tr_b16 v[240:241], v205 offset:5120
	ds_read_b64_tr_b16 v[242:243], v205 offset:7168
	v_exp_f32_e32 v225, v104
	v_exp_f32_e32 v227, v105
	s_waitcnt lgkmcnt(9)
	v_mfma_f32_32x32x16_bf16 v[16:31], v[168:171], v[244:247], v[16:31]
	ds_read_b64_tr_b16 v[244:245], v205 offset:9216
	ds_read_b64_tr_b16 v[246:247], v205 offset:11264
	v_lshl_add_u64 v[156:157], v[190:191], 0, v[252:253]
	v_lshl_add_u64 v[144:145], v[156:157], 0, s[98:99]
	global_load_dwordx4 v[156:159], v[156:157], off
	global_load_dwordx4 v[144:147], v[144:145], off
	v_exp_f32_e32 v224, v106
	v_exp_f32_e32 v226, v107
	s_waitcnt lgkmcnt(8)
	v_mfma_f32_32x32x16_bf16 v[16:31], v[172:175], v[248:251], v[16:31]
	ds_read_b64_tr_b16 v[248:249], v205 offset:13312
	ds_read_b64_tr_b16 v[250:251], v205 offset:15360
	v_exp_f32_e32 v221, v108
	v_exp_f32_e32 v223, v109
	s_waitcnt lgkmcnt(7)
	v_mfma_f32_32x32x16_bf16 v[32:47], v[160:163], v[236:239], v[32:47]
	ds_read_b64_tr_b16 v[236:237], v205 offset:1536
	ds_read_b64_tr_b16 v[238:239], v205 offset:3584
	v_lshl_add_u64 v[190:191], v[190:191], 0, s[100:101]
	v_lshl_add_u64 v[148:149], v[190:191], 0, s[98:99]
	global_load_dwordx4 v[152:155], v[190:191], off offset:-512
	global_load_dwordx4 v[148:151], v[148:149], off offset:-512
	v_exp_f32_e32 v181, v110
	v_exp_f32_e32 v222, v111
	s_waitcnt lgkmcnt(6)
	v_mfma_f32_32x32x16_bf16 v[32:47], v[164:167], v[240:243], v[32:47]
	ds_read_b64_tr_b16 v[240:241], v205 offset:5632
	ds_read_b64_tr_b16 v[242:243], v205 offset:7680
	v_exp_f32_e32 v64, v64
	v_exp_f32_e32 v65, v65
	s_waitcnt lgkmcnt(6)
	v_mfma_f32_32x32x16_bf16 v[32:47], v[168:171], v[244:247], v[32:47]
	ds_read_b64_tr_b16 v[244:245], v205 offset:9728
	ds_read_b64_tr_b16 v[246:247], v205 offset:11776
	v_exp_f32_e32 v66, v66
	v_exp_f32_e32 v67, v67
	s_waitcnt lgkmcnt(6)
	v_mfma_f32_32x32x16_bf16 v[32:47], v[172:175], v[248:251], v[32:47]
	ds_read_b64_tr_b16 v[248:249], v205 offset:13824
	ds_read_b64_tr_b16 v[250:251], v205 offset:15872
	v_exp_f32_e32 v68, v68
	v_exp_f32_e32 v69, v69
	s_waitcnt lgkmcnt(6)
	v_mfma_f32_32x32x16_bf16 v[48:63], v[160:163], v[236:239], v[48:63]
	v_exp_f32_e32 v70, v70
	v_exp_f32_e32 v71, v71
	s_waitcnt lgkmcnt(4)
	v_mfma_f32_32x32x16_bf16 v[48:63], v[164:167], v[240:243], v[48:63]
	v_exp_f32_e32 v72, v72
	v_exp_f32_e32 v73, v73
	v_exp_f32_e32 v74, v74
	s_waitcnt lgkmcnt(2)
	v_mfma_f32_32x32x16_bf16 v[48:63], v[168:171], v[244:247], v[48:63]
	v_exp_f32_e32 v75, v75
	v_exp_f32_e32 v76, v76
	v_exp_f32_e32 v77, v77
	s_waitcnt lgkmcnt(0)
	v_mfma_f32_32x32x16_bf16 v[48:63], v[172:175], v[248:251], v[48:63]
	v_exp_f32_e32 v78, v78
	v_exp_f32_e32 v79, v79
	s_waitcnt lgkmcnt(0)
	s_add_i32 s22, s39, 2
	s_cmp_ge_u32 s39, s33
	s_barrier
	s_cbranch_scc1 .Lat2_tail
	s_mov_b32 s39, s22
	s_branch .LBB0_490

; #define SBAR() __builtin_amdgcn_sched_barrier(0)
; template <int D0> __device__ __forceinline__ void pv_one(f32x16& od, int vb, bf16x8 pa0, bf16x8 pa1, bf16x8 pa2, bf16x8 pa3) {
;     const s16x4 l0 = tr_read<v_rd_off(D0, 0, 0)>(vb), h0 = tr_read<v_rd_off(D0, 0, 1)>(vb), l1 = tr_read<v_rd_off(D0, 1, 0)>(vb), h1 = tr_read<v_rd_off(D0, 1, 1)>(vb);
;     const s16x4 l2 = tr_read<v_rd_off(D0, 2, 0)>(vb), h2 = tr_read<v_rd_off(D0, 2, 1)>(vb), l3 = tr_read<v_rd_off(D0, 3, 0)>(vb), h3 = tr_read<v_rd_off(D0, 3, 1)>(vb);
;     asm volatile("s_waitcnt lgkmcnt(0)" ::: "memory"); SBAR();
;     ...
;     od = __builtin_amdgcn_mfma_f32_32x32x16_bf16(pa0, PK(l0, h0), od, 0, 0, 0);
;     od = __builtin_amdgcn_mfma_f32_32x32x16_bf16(pa1, PK(l1, h1), od, 0, 0, 0);
;     od = __builtin_amdgcn_mfma_f32_32x32x16_bf16(pa2, PK(l2, h2), od, 0, 0, 0);
;     od = __builtin_amdgcn_mfma_f32_32x32x16_bf16(pa3, PK(l3, h3), od, 0, 0, 0);
;     ...
; }
; __device__ __forceinline__ void pv_d0(f32x16* o, int vb, bf16x8 pa0, bf16x8 pa1, bf16x8 pa2, bf16x8 pa3) {
;     pv_one<0>(o[0], vb, pa0, pa1, pa2, pa3); pv_one<1>(o[1], vb, pa0, pa1, pa2, pa3); pv_one<2>(o[2], vb, pa0, pa1, pa2, pa3); pv_one<3>(o[3], vb, pa0, pa1, pa2, pa3);
.Lat2_noshift_TA:
	s_waitcnt lgkmcnt(6)
	v_mfma_f32_32x32x16_bf16 v[0:15], v[160:163], v[236:239], v[0:15]
	ds_read_b64_tr_b16 v[236:237], v206 offset:512
	ds_read_b64_tr_b16 v[238:239], v206 offset:2560
	s_waitcnt lgkmcnt(6)
	v_mfma_f32_32x32x16_bf16 v[0:15], v[164:167], v[240:243], v[0:15]
	ds_read_b64_tr_b16 v[240:241], v206 offset:4608
	ds_read_b64_tr_b16 v[242:243], v206 offset:6656
	s_waitcnt vmcnt(0)
	ds_write_b128 v207, v[144:147] offset:16384
	v_exp_f32_e32 v181, v96
	v_exp_f32_e32 v221, v97
	s_waitcnt lgkmcnt(7)
	v_mfma_f32_32x32x16_bf16 v[0:15], v[168:171], v[244:247], v[0:15]
	ds_read_b64_tr_b16 v[244:245], v206 offset:8704
	ds_read_b64_tr_b16 v[246:247], v206 offset:10752
	ds_write_b128 v207, v[156:159] offset:24576
	v_exp_f32_e32 v222, v98
	v_exp_f32_e32 v223, v99
	s_waitcnt lgkmcnt(8)
	v_mfma_f32_32x32x16_bf16 v[0:15], v[172:175], v[248:251], v[0:15]
	ds_read_b64_tr_b16 v[248:249], v206 offset:12800
	ds_read_b64_tr_b16 v[250:251], v206 offset:14848
	v_exp_f32_e32 v224, v100
	v_exp_f32_e32 v225, v101
	s_waitcnt lgkmcnt(8)
	v_mfma_f32_32x32x16_bf16 v[16:31], v[160:163], v[236:239], v[16:31]
	ds_read_b64_tr_b16 v[236:237], v206 offset:1024
	ds_read_b64_tr_b16 v[238:239], v206 offset:3072
	v_exp_f32_e32 v226, v102
	v_exp_f32_e32 v227, v103
	s_waitcnt lgkmcnt(8)
	v_mfma_f32_32x32x16_bf16 v[16:31], v[164:167], v[240:243], v[16:31]
	ds_read_b64_tr_b16 v[240:241], v206 offset:5120
	ds_read_b64_tr_b16 v[242:243], v206 offset:7168
	v_exp_f32_e32 v228, v104
	v_exp_f32_e32 v229, v105
	s_waitcnt lgkmcnt(7)
	v_mfma_f32_32x32x16_bf16 v[16:31], v[168:171], v[244:247], v[16:31]
	ds_read_b64_tr_b16 v[244:245], v206 offset:9216
	ds_read_b64_tr_b16 v[246:247], v206 offset:11264
	v_exp_f32_e32 v230, v106
	v_exp_f32_e32 v231, v107
	s_waitcnt lgkmcnt(6)
	v_mfma_f32_32x32x16_bf16 v[16:31], v[172:175], v[248:251], v[16:31]
	ds_read_b64_tr_b16 v[248:249], v206 offset:13312
	ds_read_b64_tr_b16 v[250:251], v206 offset:15360
	v_exp_f32_e32 v232, v108
	v_exp_f32_e32 v233, v109
	s_waitcnt lgkmcnt(6)
	v_mfma_f32_32x32x16_bf16 v[32:47], v[160:163], v[236:239], v[32:47]
	ds_read_b64_tr_b16 v[236:237], v206 offset:1536
	ds_read_b64_tr_b16 v[238:239], v206 offset:3584
	v_exp_f32_e32 v234, v110
	v_exp_f32_e32 v235, v111
	s_waitcnt lgkmcnt(6)
	v_mfma_f32_32x32x16_bf16 v[32:47], v[164:167], v[240:243], v[32:47]
	ds_read_b64_tr_b16 v[240:241], v206 offset:5632
	ds_read_b64_tr_b16 v[242:243], v206 offset:7680
	v_exp_f32_e32 v80, v80
	v_exp_f32_e32 v81, v81
	s_waitcnt lgkmcnt(6)
	v_mfma_f32_32x32x16_bf16 v[32:47], v[168:171], v[244:247], v[32:47]
	ds_read_b64_tr_b16 v[244:245], v206 offset:9728
	ds_read_b64_tr_b16 v[246:247], v206 offset:11776
	v_exp_f32_e32 v82, v82
	v_exp_f32_e32 v83, v83
	s_waitcnt lgkmcnt(6)
	v_mfma_f32_32x32x16_bf16 v[32:47], v[172:175], v[248:251], v[32:47]
	ds_read_b64_tr_b16 v[248:249], v206 offset:13824
	ds_read_b64_tr_b16 v[250:251], v206 offset:15872
	v_exp_f32_e32 v84, v84
	v_exp_f32_e32 v85, v85
	s_waitcnt lgkmcnt(6)
	v_mfma_f32_32x32x16_bf16 v[48:63], v[160:163], v[236:239], v[48:63]
	v_exp_f32_e32 v86, v86
	v_exp_f32_e32 v87, v87
	s_waitcnt lgkmcnt(4)
	v_mfma_f32_32x32x16_bf16 v[48:63], v[164:167], v[240:243], v[48:63]
	v_exp_f32_e32 v88, v88
	v_exp_f32_e32 v89, v89
	v_exp_f32_e32 v90, v90
	s_waitcnt lgkmcnt(2)
	v_mfma_f32_32x32x16_bf16 v[48:63], v[168:171], v[244:247], v[48:63]
	v_exp_f32_e32 v91, v91
	v_exp_f32_e32 v92, v92
	v_exp_f32_e32 v93, v93
	s_waitcnt lgkmcnt(0)
	v_mfma_f32_32x32x16_bf16 v[48:63], v[172:175], v[248:251], v[48:63]
	v_exp_f32_e32 v94, v94
	v_exp_f32_e32 v95, v95
	s_waitcnt lgkmcnt(0)
	s_barrier
; #define SBAR() __builtin_amdgcn_sched_barrier(0)
; __device__ __forceinline__ void finishSM(f32x16& p0, f32x16& p1, float alpha, float& l_reg, bf16x8& pa0, bf16x8& pa1, bf16x8& pa2, bf16x8& pa3) {
;     for (int r = 0; r < 16; ++r) p1[r] = __builtin_amdgcn_exp2f(p1[r]);
;     float ps = 0; for (int r = 0; r < 16; ++r) ps += p0[r]; for (int r = 0; r < 16; ++r) ps += p1[r];
;     { auto rr = __builtin_amdgcn_permlane32_swap(__float_as_uint(ps), __float_as_uint(ps), false, false);
;       ps = __uint_as_float(rr[0]) + __uint_as_float(rr[1]); }
;     l_reg = l_reg * alpha + ps;
;     ...
;     PK4(p0, 0, pa0); PK4(p0, 8, pa1); PK4(p1, 0, pa2); PK4(p1, 8, pa3);
;     ...
; }
; template <int D0> __device__ __forceinline__ void pv_one(f32x16& od, int vb, bf16x8 pa0, bf16x8 pa1, bf16x8 pa2, bf16x8 pa3) {
;     const s16x4 l0 = tr_read<v_rd_off(D0, 0, 0)>(vb), h0 = tr_read<v_rd_off(D0, 0, 1)>(vb), l1 = tr_read<v_rd_off(D0, 1, 0)>(vb), h1 = tr_read<v_rd_off(D0, 1, 1)>(vb);
;     const s16x4 l2 = tr_read<v_rd_off(D0, 2, 0)>(vb), h2 = tr_read<v_rd_off(D0, 2, 1)>(vb), l3 = tr_read<v_rd_off(D0, 3, 0)>(vb), h3 = tr_read<v_rd_off(D0, 3, 1)>(vb);
;     asm volatile("s_waitcnt lgkmcnt(0)" ::: "memory"); SBAR();
;     ...
;     od = __builtin_amdgcn_mfma_f32_32x32x16_bf16(pa0, PK(l0, h0), od, 0, 0, 0);
;     od = __builtin_amdgcn_mfma_f32_32x32x16_bf16(pa1, PK(l1, h1), od, 0, 0, 0);
;     od = __builtin_amdgcn_mfma_f32_32x32x16_bf16(pa2, PK(l2, h2), od, 0, 0, 0);
;     od = __builtin_amdgcn_mfma_f32_32x32x16_bf16(pa3, PK(l3, h3), od, 0, 0, 0);
;     ...
; }
; __device__ __forceinline__ void pv_d0(f32x16* o, int vb, bf16x8 pa0, bf16x8 pa1, bf16x8 pa2, bf16x8 pa3) {
;     pv_one<0>(o[0], vb, pa0, pa1, pa2, pa3); pv_one<1>(o[1], vb, pa0, pa1, pa2, pa3); pv_one<2>(o[2], vb, pa0, pa1, pa2, pa3); pv_one<3>(o[3], vb, pa0, pa1, pa2, pa3);
	ds_read_b64_tr_b16 v[236:237], v205 offset:0
	ds_read_b64_tr_b16 v[238:239], v205 offset:2048
	ds_read_b64_tr_b16 v[240:241], v205 offset:4096
	ds_read_b64_tr_b16 v[242:243], v205 offset:6144
	ds_read_b64_tr_b16 v[244:245], v205 offset:8192
	ds_read_b64_tr_b16 v[246:247], v205 offset:10240
	ds_read_b64_tr_b16 v[248:249], v205 offset:12288
	ds_read_b64_tr_b16 v[250:251], v205 offset:14336
	v_add_f32_e32 v219, v181, v221
	v_cvt_pk_bf16_f32 v160, v181, v221
	v_add_f32_e32 v219, v222, v219
	v_cvt_pk_bf16_f32 v161, v222, v223
	v_add_f32_e32 v219, v223, v219
	v_cvt_pk_bf16_f32 v162, v224, v225
	v_add_f32_e32 v219, v224, v219
	v_cvt_pk_bf16_f32 v163, v226, v227
	v_add_f32_e32 v219, v225, v219
	v_cvt_pk_bf16_f32 v164, v228, v229
	v_add_f32_e32 v219, v226, v219
	v_cvt_pk_bf16_f32 v165, v230, v231
	v_add_f32_e32 v219, v227, v219
	v_cvt_pk_bf16_f32 v166, v232, v233
	v_add_f32_e32 v219, v228, v219
	v_cvt_pk_bf16_f32 v167, v234, v235
	v_add_f32_e32 v219, v229, v219
	v_cvt_pk_bf16_f32 v168, v80, v81
	v_add_f32_e32 v219, v230, v219
	v_cvt_pk_bf16_f32 v169, v82, v83
	v_add_f32_e32 v219, v231, v219
	v_cvt_pk_bf16_f32 v170, v84, v85
	v_add_f32_e32 v219, v232, v219
	v_cvt_pk_bf16_f32 v171, v86, v87
	v_add_f32_e32 v219, v233, v219
	v_cvt_pk_bf16_f32 v172, v88, v89
	v_add_f32_e32 v219, v234, v219
	v_cvt_pk_bf16_f32 v173, v90, v91
	v_add_f32_e32 v219, v235, v219
	v_cvt_pk_bf16_f32 v174, v92, v93
	v_add_f32_e32 v219, v80, v219
	v_cvt_pk_bf16_f32 v175, v94, v95
	v_add_f32_e32 v219, v81, v219
	v_permlane32_swap_b32_e32 v160, v162
	v_add_f32_e32 v219, v82, v219
	v_permlane32_swap_b32_e32 v161, v163
	v_add_f32_e32 v219, v83, v219
	v_permlane32_swap_b32_e32 v164, v166
	v_add_f32_e32 v219, v84, v219
	v_permlane32_swap_b32_e32 v165, v167
	v_add_f32_e32 v219, v85, v219
	v_permlane32_swap_b32_e32 v168, v170
	v_add_f32_e32 v219, v86, v219
	v_permlane32_swap_b32_e32 v169, v171
	v_add_f32_e32 v219, v87, v219
	v_permlane32_swap_b32_e32 v172, v174
	v_add_f32_e32 v219, v88, v219
	v_permlane32_swap_b32_e32 v173, v175
	v_add_f32_e32 v219, v89, v219
	v_add_f32_e32 v219, v90, v219
	v_add_f32_e32 v219, v91, v219
	v_add_f32_e32 v219, v92, v219
	v_add_f32_e32 v219, v93, v219
	v_add_f32_e32 v219, v94, v219
	v_add_f32_e32 v219, v95, v219
	v_mov_b32_e32 v220, v219
	s_nop 1
	v_permlane32_swap_b32_e32 v219, v220
	v_add_f32_e32 v219, v219, v220
	v_add_f32_e32 v204, v204, v219
	s_waitcnt lgkmcnt(6)
	v_mfma_f32_32x32x16_bf16 v[0:15], v[160:163], v[236:239], v[0:15]
	ds_read_b64_tr_b16 v[236:237], v205 offset:512
	ds_read_b64_tr_b16 v[238:239], v205 offset:2560
	s_waitcnt lgkmcnt(6)
	v_mfma_f32_32x32x16_bf16 v[0:15], v[164:167], v[240:243], v[0:15]
	ds_read_b64_tr_b16 v[240:241], v205 offset:4608
	ds_read_b64_tr_b16 v[242:243], v205 offset:6656
	s_waitcnt lgkmcnt(6)
	v_mfma_f32_32x32x16_bf16 v[0:15], v[168:171], v[244:247], v[0:15]
	ds_read_b64_tr_b16 v[244:245], v205 offset:8704
	ds_read_b64_tr_b16 v[246:247], v205 offset:10752
	s_waitcnt lgkmcnt(6)
	v_mfma_f32_32x32x16_bf16 v[0:15], v[172:175], v[248:251], v[0:15]
	ds_read_b64_tr_b16 v[248:249], v205 offset:12800
	ds_read_b64_tr_b16 v[250:251], v205 offset:14848
	s_waitcnt lgkmcnt(6)
	v_mfma_f32_32x32x16_bf16 v[16:31], v[160:163], v[236:239], v[16:31]
	ds_read_b64_tr_b16 v[236:237], v205 offset:1024
	ds_read_b64_tr_b16 v[238:239], v205 offset:3072
	s_waitcnt lgkmcnt(6)
	v_mfma_f32_32x32x16_bf16 v[16:31], v[164:167], v[240:243], v[16:31]
	ds_read_b64_tr_b16 v[240:241], v205 offset:5120
	ds_read_b64_tr_b16 v[242:243], v205 offset:7168
	s_waitcnt lgkmcnt(6)
	v_mfma_f32_32x32x16_bf16 v[16:31], v[168:171], v[244:247], v[16:31]
	ds_read_b64_tr_b16 v[244:245], v205 offset:9216
	ds_read_b64_tr_b16 v[246:247], v205 offset:11264
	s_waitcnt lgkmcnt(6)
	v_mfma_f32_32x32x16_bf16 v[16:31], v[172:175], v[248:251], v[16:31]
	ds_read_b64_tr_b16 v[248:249], v205 offset:13312
	ds_read_b64_tr_b16 v[250:251], v205 offset:15360
	s_waitcnt lgkmcnt(6)
	v_mfma_f32_32x32x16_bf16 v[32:47], v[160:163], v[236:239], v[32:47]
	ds_read_b64_tr_b16 v[236:237], v205 offset:1536
	ds_read_b64_tr_b16 v[238:239], v205 offset:3584
	s_waitcnt lgkmcnt(6)
	v_mfma_f32_32x32x16_bf16 v[32:47], v[164:167], v[240:243], v[32:47]
	ds_read_b64_tr_b16 v[240:241], v205 offset:5632
	ds_read_b64_tr_b16 v[242:243], v205 offset:7680
	s_waitcnt lgkmcnt(6)
	v_mfma_f32_32x32x16_bf16 v[32:47], v[168:171], v[244:247], v[32:47]
	ds_read_b64_tr_b16 v[244:245], v205 offset:9728
	ds_read_b64_tr_b16 v[246:247], v205 offset:11776
	s_waitcnt lgkmcnt(6)
	v_mfma_f32_32x32x16_bf16 v[32:47], v[172:175], v[248:251], v[32:47]
	ds_read_b64_tr_b16 v[248:249], v205 offset:13824
	ds_read_b64_tr_b16 v[250:251], v205 offset:15872
	s_waitcnt lgkmcnt(6)
	v_mfma_f32_32x32x16_bf16 v[48:63], v[160:163], v[236:239], v[48:63]
	s_waitcnt lgkmcnt(4)
	v_mfma_f32_32x32x16_bf16 v[48:63], v[164:167], v[240:243], v[48:63]
	s_waitcnt lgkmcnt(2)
	v_mfma_f32_32x32x16_bf16 v[48:63], v[168:171], v[244:247], v[48:63]
	s_waitcnt lgkmcnt(0)
	v_mfma_f32_32x32x16_bf16 v[48:63], v[172:175], v[248:251], v[48:63]
